# per-XCD mix queue class order changed to longest-first: tails, AL, HL, G, HC, PL, AC, transposes
# speedup vs baseline: 1.0034x; 1.0005x over previous
.LBB0_641:
	s_or_b64 exec, exec, s[36:37]
	v_mov_b32_e32 v0, s1
	s_waitcnt lgkmcnt(0)
	s_barrier
	ds_read_b32 v0, v0
	s_mov_b64 s[36:37], -1
	s_waitcnt lgkmcnt(0)
	v_cmp_le_i32_e32 vcc, s15, v0
	v_readfirstlane_b32 s18, v0
	s_cbranch_vccnz .LBB0_636
	v_readlane_b32 s100, v254, 0
	s_nop 3
	v_readlane_b32 s19, v254, 2
	v_readlane_b32 s42, v254, 3
	s_nop 3
	s_mul_i32 s101, s100, s19
	s_add_i32 s101, s101, s42
	s_lshl_b32 s19, s100, 4
	s_add_i32 s42, s19, 472
	s_cmpk_lt_u32 s18, 120
	s_cselect_b32 s101, s42, s101
	s_add_i32 s42, s19, 744
	s_cmpk_lt_u32 s18, 104
	s_cselect_b32 s101, s42, s101
	s_lshl_b32 s42, s100, 5
	s_addk_i32 s42, 264
	s_cmpk_lt_u32 s18, 88
	s_cselect_b32 s101, s42, s101
	s_add_i32 s42, s19, 664
	s_cmpk_lt_u32 s18, 56
	s_cselect_b32 s101, s42, s101
	s_add_i32 s42, s19, 40
	s_cmpk_lt_u32 s18, 40
	s_cselect_b32 s101, s42, s101
	s_add_i32 s42, s19, 184
	s_cmpk_lt_u32 s18, 24
	s_cselect_b32 s101, s42, s101
	s_lshl_b32 s42, s100, 3
	s_cmpk_lt_u32 s18, 8
	s_cselect_b32 s101, s42, s101
	s_add_i32 s18, s18, s101
	s_cmp_gt_i32 s18, 63
	s_cbranch_scc0 .LBB0_840
	s_lshl_b32 s42, s18, 1
	v_readlane_b32 s19, v251, 54
	s_add_i32 s19, s19, s42
	s_cmpk_gt_i32 s19, 0xff
	s_cbranch_scc0 .LBB0_775
	s_cmpk_gt_u32 s19, 0x1ff
	s_cbranch_scc0 .LBB0_751
	s_cmpk_gt_u32 s19, 0x3ff
	s_cbranch_scc0 .LBB0_704
	s_cmpk_gt_u32 s19, 0x4ff
	s_cbranch_scc0 .LBB0_696
	s_cmpk_gt_u32 s19, 0x5ff
	s_cbranch_scc0 .LBB0_673
	s_cmpk_gt_u32 s19, 0x6ff
	s_cbranch_scc0 .LBB0_654
	s_cmpk_gt_u32 s19, 0xa3f
	s_cbranch_scc0 .LBB0_651
	s_lshl_b32 s20, s19, 3
	s_and_b32 s20, s20, 0x7fffffc0
	s_add_i32 s70, s20, 0xffffae00
	s_lshl_b32 s20, s19, 8
	v_mov_b32_e32 v2, v189
	s_and_b32 s20, s20, 0x700
	s_lshl_b32 s21, s20, 2
	v_ashrrev_i32_e32 v3, 6, v2
	v_readlane_b32 s22, v252, 45
	v_add_u32_e32 v0, s70, v3
	s_add_u32 s22, s22, s21
	v_readlane_b32 s21, v252, 46
	v_lshlrev_b32_e32 v1, 4, v2
	s_addc_u32 s23, s21, 0
	v_and_b32_e32 v160, 0x3f0, v1
	v_ashrrev_i32_e32 v1, 31, v0
	v_lshl_add_u64 v[4:5], s[22:23], 0, v[160:161]
	v_lshlrev_b64 v[0:1], 13, v[0:1]
	v_lshl_add_u64 v[0:1], v[4:5], 0, v[0:1]
	global_load_dwordx4 v[24:27], v[0:1], off
	s_mov_b64 s[100:101], 0x8000
	v_lshl_add_u64 v[4:5], v[0:1], 0, s[100:101]
	global_load_dwordx4 v[28:31], v[4:5], off
	v_lshl_add_u64 v[4:5], v[4:5], 0, s[100:101]
	global_load_dwordx4 v[32:35], v[4:5], off
	v_lshl_add_u64 v[4:5], v[4:5], 0, s[100:101]
	global_load_dwordx4 v[36:39], v[4:5], off
	v_lshl_add_u64 v[4:5], v[4:5], 0, s[100:101]
	global_load_dwordx4 v[40:43], v[4:5], off
	v_lshl_add_u64 v[4:5], v[4:5], 0, s[100:101]
	global_load_dwordx4 v[44:47], v[4:5], off
	v_lshl_add_u64 v[4:5], v[4:5], 0, s[100:101]
	global_load_dwordx4 v[48:51], v[4:5], off
	v_lshl_add_u64 v[4:5], v[4:5], 0, s[100:101]
	global_load_dwordx4 v[52:55], v[4:5], off
	v_lshl_add_u64 v[4:5], v[4:5], 0, s[100:101]
	global_load_dwordx4 v[56:59], v[4:5], off
	v_lshl_add_u64 v[4:5], v[4:5], 0, s[100:101]
	global_load_dwordx4 v[60:63], v[4:5], off
	v_lshl_add_u64 v[4:5], v[4:5], 0, s[100:101]
	global_load_dwordx4 v[64:67], v[4:5], off
	v_lshl_add_u64 v[4:5], v[4:5], 0, s[100:101]
	global_load_dwordx4 v[68:71], v[4:5], off
	v_lshl_add_u64 v[4:5], v[4:5], 0, s[100:101]
	global_load_dwordx4 v[72:75], v[4:5], off
	v_lshl_add_u64 v[4:5], v[4:5], 0, s[100:101]
	global_load_dwordx4 v[76:79], v[4:5], off
	v_lshl_add_u64 v[4:5], v[4:5], 0, s[100:101]
	global_load_dwordx4 v[80:83], v[4:5], off
	v_lshl_add_u64 v[4:5], v[4:5], 0, s[100:101]
	global_load_dwordx4 v[84:87], v[4:5], off
	s_movk_i32 s36, 0x404
	v_mul_lo_u32 v3, v3, s36
	v_add3_u32 v3, s17, v160, v3
	s_lshl_b64 s[22:23], s[70:71], 1
	v_readlane_b32 s21, v252, 47
	s_nop 0
	s_add_u32 s22, s21, s22
	v_readlane_b32 s21, v252, 48
	s_nop 0
	s_addc_u32 s23, s21, s23
	s_waitcnt vmcnt(15)
	ds_write2_b32 v3, v24, v25 offset1:1
	ds_write2_b32 v3, v26, v27 offset0:2 offset1:3
	s_waitcnt vmcnt(14)
	v_add_u32_e32 v8, 0x1010, v3
	ds_write2_b32 v8, v28, v29 offset1:1
	ds_write2_b32 v8, v30, v31 offset0:2 offset1:3
	s_waitcnt vmcnt(13)
	v_add_u32_e32 v8, 0x2020, v3
	ds_write2_b32 v8, v32, v33 offset1:1
	ds_write2_b32 v8, v34, v35 offset0:2 offset1:3
	s_waitcnt vmcnt(12)
	v_add_u32_e32 v8, 0x3030, v3
	ds_write2_b32 v8, v36, v37 offset1:1
	ds_write2_b32 v8, v38, v39 offset0:2 offset1:3
	s_waitcnt vmcnt(11)
	v_add_u32_e32 v8, 0x4040, v3
	ds_write2_b32 v8, v40, v41 offset1:1
	ds_write2_b32 v8, v42, v43 offset0:2 offset1:3
	s_waitcnt vmcnt(10)
	v_add_u32_e32 v8, 0x5050, v3
	ds_write2_b32 v8, v44, v45 offset1:1
	ds_write2_b32 v8, v46, v47 offset0:2 offset1:3
	s_waitcnt vmcnt(9)
	v_add_u32_e32 v8, 0x6060, v3
	ds_write2_b32 v8, v48, v49 offset1:1
	ds_write2_b32 v8, v50, v51 offset0:2 offset1:3
	s_waitcnt vmcnt(8)
	v_add_u32_e32 v8, 0x7070, v3
	ds_write2_b32 v8, v52, v53 offset1:1
	ds_write2_b32 v8, v54, v55 offset0:2 offset1:3
	s_waitcnt vmcnt(7)
	v_add_u32_e32 v8, 0x8080, v3
	ds_write2_b32 v8, v56, v57 offset1:1
	ds_write2_b32 v8, v58, v59 offset0:2 offset1:3
	s_waitcnt vmcnt(6)
	v_add_u32_e32 v8, 0x9090, v3
	ds_write2_b32 v8, v60, v61 offset1:1
	ds_write2_b32 v8, v62, v63 offset0:2 offset1:3
	s_waitcnt vmcnt(5)
	v_add_u32_e32 v8, 0xa0a0, v3
	ds_write2_b32 v8, v64, v65 offset1:1
	ds_write2_b32 v8, v66, v67 offset0:2 offset1:3
	s_waitcnt vmcnt(4)
	v_add_u32_e32 v8, 0xb0b0, v3
	ds_write2_b32 v8, v68, v69 offset1:1
	ds_write2_b32 v8, v70, v71 offset0:2 offset1:3
	s_waitcnt vmcnt(3)
	v_add_u32_e32 v8, 0xc0c0, v3
	ds_write2_b32 v8, v72, v73 offset1:1
	ds_write2_b32 v8, v74, v75 offset0:2 offset1:3
	s_waitcnt vmcnt(2)
	v_add_u32_e32 v8, 0xd0d0, v3
	ds_write2_b32 v8, v76, v77 offset1:1
	ds_write2_b32 v8, v78, v79 offset0:2 offset1:3
	s_waitcnt vmcnt(1)
	v_add_u32_e32 v8, 0xe0e0, v3
	ds_write2_b32 v8, v80, v81 offset1:1
	ds_write2_b32 v8, v82, v83 offset0:2 offset1:3
	s_waitcnt vmcnt(0)
	v_add_u32_e32 v8, 0xf0f0, v3
	ds_write2_b32 v8, v84, v85 offset1:1
	ds_write2_b32 v8, v86, v87 offset0:2 offset1:3
	v_lshlrev_b32_e32 v0, 3, v2
	v_and_b32_e32 v3, 56, v0
	v_mov_b32_e32 v4, s17
	v_lshlrev_b32_e32 v160, 1, v3
	v_ashrrev_i32_e32 v8, 3, v2
	v_mad_u32_u24 v3, v3, s36, v4
	v_lshl_add_u32 v4, v8, 2, v3
	s_waitcnt lgkmcnt(0)
	s_barrier
	ds_read_b32 v5, v4
	ds_read_b32 v6, v4 offset:1028
	ds_read_b32 v7, v4 offset:2056
	ds_read_b32 v9, v4 offset:3084
	ds_read_b32 v10, v4 offset:4112
	ds_read_b32 v11, v4 offset:5140
	ds_read_b32 v12, v4 offset:6168
	ds_read_b32 v4, v4 offset:7196
	s_waitcnt lgkmcnt(4)
	v_bfe_u32 v20, v5, 16, 1
	v_add3_u32 v20, v5, v20, s94
	v_cvt_pk_bf16_f32 v9, v7, v9
	v_add_u32_e32 v8, s20, v8
	s_waitcnt lgkmcnt(0)
	v_bfe_u32 v19, v6, 16, 1
	v_mov_b32_e32 v5, v9
	v_ashrrev_i32_e32 v9, 31, v8
	v_lshl_add_u64 v[0:1], s[22:23], 0, v[160:161]
	v_add3_u32 v19, v6, v19, s94
	v_cvt_pk_bf16_f32 v10, v10, v11
	v_cvt_pk_bf16_f32 v4, v12, v4
	v_lshlrev_b64 v[8:9], 12, v[8:9]
	v_mov_b32_e32 v7, v4
	v_mov_b32_e32 v6, v10
	v_perm_b32 v4, v19, v20, s95
	v_lshl_add_u64 v[8:9], v[0:1], 0, v[8:9]
	global_store_dwordx4 v[8:9], v[4:7], off
	s_mov_b64 s[36:37], 0
	s_nop 0
	v_add_u32_e32 v4, 0x100, v2
	v_ashrrev_i32_e32 v8, 3, v4
	v_lshl_add_u32 v4, v8, 2, v3
	ds_read_b32 v5, v4
	ds_read_b32 v6, v4 offset:1028
	ds_read_b32 v7, v4 offset:2056
	ds_read_b32 v9, v4 offset:3084
	ds_read_b32 v10, v4 offset:4112
	ds_read_b32 v11, v4 offset:5140
	ds_read_b32 v12, v4 offset:6168
	ds_read_b32 v4, v4 offset:7196
	s_waitcnt lgkmcnt(4)
	v_bfe_u32 v20, v5, 16, 1
	v_add3_u32 v20, v5, v20, s94
	v_cvt_pk_bf16_f32 v9, v7, v9
	v_add_u32_e32 v8, s20, v8
	s_waitcnt lgkmcnt(0)
	v_bfe_u32 v19, v6, 16, 1
	v_mov_b32_e32 v5, v9
	v_ashrrev_i32_e32 v9, 31, v8
	v_add3_u32 v19, v6, v19, s94
	v_cvt_pk_bf16_f32 v10, v10, v11
	v_cvt_pk_bf16_f32 v4, v12, v4
	v_lshlrev_b64 v[8:9], 12, v[8:9]
	v_mov_b32_e32 v7, v4
	v_mov_b32_e32 v6, v10
	v_perm_b32 v4, v19, v20, s95
	v_lshl_add_u64 v[8:9], v[0:1], 0, v[8:9]
	global_store_dwordx4 v[8:9], v[4:7], off
	s_nop 1
	v_add_u32_e32 v4, 0x200, v2
	v_ashrrev_i32_e32 v8, 3, v4
	v_lshl_add_u32 v4, v8, 2, v3
	ds_read_b32 v5, v4
	ds_read_b32 v6, v4 offset:1028
	ds_read_b32 v7, v4 offset:2056
	ds_read_b32 v9, v4 offset:3084
	ds_read_b32 v10, v4 offset:4112
	ds_read_b32 v11, v4 offset:5140
	ds_read_b32 v12, v4 offset:6168
	ds_read_b32 v4, v4 offset:7196
	s_waitcnt lgkmcnt(4)
	v_bfe_u32 v20, v5, 16, 1
	v_add3_u32 v20, v5, v20, s94
	v_cvt_pk_bf16_f32 v9, v7, v9
	v_add_u32_e32 v8, s20, v8
	s_waitcnt lgkmcnt(0)
	v_bfe_u32 v19, v6, 16, 1
	v_mov_b32_e32 v5, v9
	v_ashrrev_i32_e32 v9, 31, v8
	v_add3_u32 v19, v6, v19, s94
	v_cvt_pk_bf16_f32 v10, v10, v11
	v_cvt_pk_bf16_f32 v4, v12, v4
	v_lshlrev_b64 v[8:9], 12, v[8:9]
	v_mov_b32_e32 v7, v4
	v_mov_b32_e32 v6, v10
	v_perm_b32 v4, v19, v20, s95
	v_lshl_add_u64 v[8:9], v[0:1], 0, v[8:9]
	global_store_dwordx4 v[8:9], v[4:7], off
	s_nop 1
	v_add_u32_e32 v4, 0x300, v2
	v_ashrrev_i32_e32 v8, 3, v4
	v_lshl_add_u32 v4, v8, 2, v3
	ds_read_b32 v5, v4
	ds_read_b32 v6, v4 offset:1028
	ds_read_b32 v7, v4 offset:2056
	ds_read_b32 v9, v4 offset:3084
	ds_read_b32 v10, v4 offset:4112
	ds_read_b32 v11, v4 offset:5140
	ds_read_b32 v12, v4 offset:6168
	ds_read_b32 v4, v4 offset:7196
	s_waitcnt lgkmcnt(4)
	v_bfe_u32 v20, v5, 16, 1
	v_add3_u32 v20, v5, v20, s94
	v_cvt_pk_bf16_f32 v9, v7, v9
	v_add_u32_e32 v8, s20, v8
	s_waitcnt lgkmcnt(0)
	v_bfe_u32 v19, v6, 16, 1
	v_mov_b32_e32 v5, v9
	v_ashrrev_i32_e32 v9, 31, v8
	v_add3_u32 v19, v6, v19, s94
	v_cvt_pk_bf16_f32 v10, v10, v11
	v_cvt_pk_bf16_f32 v4, v12, v4
	v_lshlrev_b64 v[8:9], 12, v[8:9]
	v_mov_b32_e32 v7, v4
	v_mov_b32_e32 v6, v10
	v_perm_b32 v4, v19, v20, s95
	v_lshl_add_u64 v[8:9], v[0:1], 0, v[8:9]
	global_store_dwordx4 v[8:9], v[4:7], off
	s_nop 1
	v_add_u32_e32 v4, 0x400, v2
	v_ashrrev_i32_e32 v8, 3, v4
	v_lshl_add_u32 v4, v8, 2, v3
	ds_read_b32 v5, v4
	ds_read_b32 v6, v4 offset:1028
	ds_read_b32 v7, v4 offset:2056
	ds_read_b32 v9, v4 offset:3084
	ds_read_b32 v10, v4 offset:4112
	ds_read_b32 v11, v4 offset:5140
	ds_read_b32 v12, v4 offset:6168
	ds_read_b32 v4, v4 offset:7196
	s_waitcnt lgkmcnt(4)
	v_bfe_u32 v20, v5, 16, 1
	v_add3_u32 v20, v5, v20, s94
	v_cvt_pk_bf16_f32 v9, v7, v9
	v_add_u32_e32 v8, s20, v8
	s_waitcnt lgkmcnt(0)
	v_bfe_u32 v19, v6, 16, 1
	v_mov_b32_e32 v5, v9
	v_ashrrev_i32_e32 v9, 31, v8
	v_add3_u32 v19, v6, v19, s94
	v_cvt_pk_bf16_f32 v10, v10, v11
	v_cvt_pk_bf16_f32 v4, v12, v4
	v_lshlrev_b64 v[8:9], 12, v[8:9]
	v_mov_b32_e32 v7, v4
	v_mov_b32_e32 v6, v10
	v_perm_b32 v4, v19, v20, s95
	v_lshl_add_u64 v[8:9], v[0:1], 0, v[8:9]
	global_store_dwordx4 v[8:9], v[4:7], off
	s_nop 1
	v_add_u32_e32 v4, 0x500, v2
	v_ashrrev_i32_e32 v8, 3, v4
	v_lshl_add_u32 v4, v8, 2, v3
	ds_read_b32 v5, v4
	ds_read_b32 v6, v4 offset:1028
	ds_read_b32 v7, v4 offset:2056
	ds_read_b32 v9, v4 offset:3084
	ds_read_b32 v10, v4 offset:4112
	ds_read_b32 v11, v4 offset:5140
	ds_read_b32 v12, v4 offset:6168
	ds_read_b32 v4, v4 offset:7196
	s_waitcnt lgkmcnt(4)
	v_bfe_u32 v20, v5, 16, 1
	v_add3_u32 v20, v5, v20, s94
	v_cvt_pk_bf16_f32 v9, v7, v9
	v_add_u32_e32 v8, s20, v8
	s_waitcnt lgkmcnt(0)
	v_bfe_u32 v19, v6, 16, 1
	v_mov_b32_e32 v5, v9
	v_ashrrev_i32_e32 v9, 31, v8
	v_add3_u32 v19, v6, v19, s94
	v_cvt_pk_bf16_f32 v10, v10, v11
	v_cvt_pk_bf16_f32 v4, v12, v4
	v_lshlrev_b64 v[8:9], 12, v[8:9]
	v_mov_b32_e32 v7, v4
	v_mov_b32_e32 v6, v10
	v_perm_b32 v4, v19, v20, s95
	v_lshl_add_u64 v[8:9], v[0:1], 0, v[8:9]
	global_store_dwordx4 v[8:9], v[4:7], off
	s_nop 1
	v_add_u32_e32 v4, 0x600, v2
	v_ashrrev_i32_e32 v8, 3, v4
	v_lshl_add_u32 v4, v8, 2, v3
	ds_read_b32 v5, v4
	ds_read_b32 v6, v4 offset:1028
	ds_read_b32 v7, v4 offset:2056
	ds_read_b32 v9, v4 offset:3084
	ds_read_b32 v10, v4 offset:4112
	ds_read_b32 v11, v4 offset:5140
	ds_read_b32 v12, v4 offset:6168
	ds_read_b32 v4, v4 offset:7196
	s_waitcnt lgkmcnt(4)
	v_bfe_u32 v20, v5, 16, 1
	v_add3_u32 v20, v5, v20, s94
	v_cvt_pk_bf16_f32 v9, v7, v9
	v_add_u32_e32 v8, s20, v8
	s_waitcnt lgkmcnt(0)
	v_bfe_u32 v19, v6, 16, 1
	v_mov_b32_e32 v5, v9
	v_ashrrev_i32_e32 v9, 31, v8
	v_add3_u32 v19, v6, v19, s94
	v_cvt_pk_bf16_f32 v10, v10, v11
	v_cvt_pk_bf16_f32 v4, v12, v4
	v_lshlrev_b64 v[8:9], 12, v[8:9]
	v_mov_b32_e32 v7, v4
	v_mov_b32_e32 v6, v10
	v_perm_b32 v4, v19, v20, s95
	v_lshl_add_u64 v[8:9], v[0:1], 0, v[8:9]
	v_add_u32_e32 v2, 0x700, v2
	global_store_dwordx4 v[8:9], v[4:7], off
	s_nop 1
	v_ashrrev_i32_e32 v6, 3, v2
	v_lshl_add_u32 v2, v6, 2, v3
	ds_read_b32 v3, v2
	ds_read_b32 v4, v2 offset:1028
	ds_read_b32 v5, v2 offset:2056
	ds_read_b32 v7, v2 offset:3084
	ds_read_b32 v8, v2 offset:4112
	ds_read_b32 v9, v2 offset:5140
	ds_read_b32 v10, v2 offset:6168
	ds_read_b32 v2, v2 offset:7196
	s_waitcnt lgkmcnt(4)
	v_bfe_u32 v18, v3, 16, 1
	v_add3_u32 v18, v3, v18, s94
	v_cvt_pk_bf16_f32 v7, v5, v7
	v_add_u32_e32 v6, s20, v6
	s_waitcnt lgkmcnt(0)
	v_bfe_u32 v17, v4, 16, 1
	v_mov_b32_e32 v3, v7
	v_ashrrev_i32_e32 v7, 31, v6
	v_add3_u32 v17, v4, v17, s94
	v_cvt_pk_bf16_f32 v8, v8, v9
	v_cvt_pk_bf16_f32 v2, v10, v2
	v_lshlrev_b64 v[6:7], 12, v[6:7]
	v_mov_b32_e32 v5, v2
	v_mov_b32_e32 v4, v8
	v_perm_b32 v2, v17, v18, s95
	v_lshl_add_u64 v[0:1], v[0:1], 0, v[6:7]
	global_store_dwordx4 v[0:1], v[2:5], off
	s_barrier
